# P0 adaLN GEMV rewritten by hand on v_mfma_f32_32x32x2_f32 (exact f32; all 64 weight loads per lane in flight, 8-way k split summed through LDS); on top of scan V LDS-DMA
# baseline (speedup 1.0000x reference)
; __device__ __forceinline__ void p_adaln(const Args& a, unsigned char* lds, const int mk_wid) {
;     ...
;     for (int i = tid; i < 17 * 1024; i += 512) { const float v = (i < 16 * 1024) ? c[i] : cctx[i - 16 * 1024]; sl[i] = v * __builtin_amdgcn_rcpf(1.f + __expf(-v)); }
;     __syncthreads();
.LBB0_8:
	v_cmp_gt_i32_e32 vcc, 1, v7
	v_cmp_lt_i32_e64 s[2:3], 0, v6
	s_lshr_b32 s70, s33, 6
	s_and_b64 s[2:3], vcc, s[2:3]
	s_and_saveexec_b64 s[12:13], s[2:3]
	s_cbranch_execz .LBB0_21
	s_load_dwordx4 s[4:7], s[0:1], 0x18
	s_load_dwordx2 s[14:15], s[0:1], 0x28
	v_mbcnt_lo_u32_b32 v8, -1, 0
	v_mbcnt_hi_u32_b32 v8, -1, v8
	s_movk_i32 s2, 0x4400
	v_add_u32_e32 v14, s72, v8
	v_cmp_gt_i32_e32 vcc, s2, v14
	s_and_saveexec_b64 s[2:3], vcc
	s_cbranch_execz .LBB0_12
	s_load_dwordx2 s[16:17], s[0:1], 0x8
	s_lshl_b32 s9, s70, 8
	s_add_i32 s9, s9, 0
	v_lshl_add_u32 v9, v8, 2, s9
	v_lshlrev_b32_e32 v2, 2, v14
	v_add_u32_e32 v10, 0x8000, v9
	s_waitcnt lgkmcnt(0)
	global_load_dword v16, v2, s[16:17]
	global_load_dword v17, v2, s[16:17] offset:2048
	v_add_u32_e32 v4, 0x1000, v2
	global_load_dword v18, v4, s[16:17]
	global_load_dword v19, v4, s[16:17] offset:2048
	v_add_u32_e32 v5, 0x2000, v2
	global_load_dword v20, v5, s[16:17]
	global_load_dword v21, v5, s[16:17] offset:2048
	v_add_u32_e32 v11, 0x3000, v2
	global_load_dword v22, v11, s[16:17]
	global_load_dword v23, v11, s[16:17] offset:2048
	v_add_u32_e32 v12, 0x4000, v2
	global_load_dword v24, v12, s[16:17]
	global_load_dword v25, v12, s[16:17] offset:2048
	v_add_u32_e32 v13, 0x5000, v2
	global_load_dword v26, v13, s[16:17]
	global_load_dword v27, v13, s[16:17] offset:2048
	v_add_u32_e32 v3, 0x6000, v2
	global_load_dword v28, v3, s[16:17]
	global_load_dword v29, v3, s[16:17] offset:2048
	v_add_u32_e32 v4, 0x7000, v2
	global_load_dword v30, v4, s[16:17]
	global_load_dword v31, v4, s[16:17] offset:2048
	v_add_u32_e32 v5, 0x8000, v2
	global_load_dword v32, v5, s[16:17]
	global_load_dword v33, v5, s[16:17] offset:2048
	v_add_u32_e32 v11, 0x9000, v2
	global_load_dword v34, v11, s[16:17]
	global_load_dword v35, v11, s[16:17] offset:2048
	v_add_u32_e32 v12, 0xa000, v2
	global_load_dword v36, v12, s[16:17]
	global_load_dword v37, v12, s[16:17] offset:2048
	v_add_u32_e32 v13, 0xb000, v2
	global_load_dword v38, v13, s[16:17]
	global_load_dword v39, v13, s[16:17] offset:2048
	v_add_u32_e32 v3, 0xc000, v2
	global_load_dword v40, v3, s[16:17]
	global_load_dword v41, v3, s[16:17] offset:2048
	v_add_u32_e32 v4, 0xd000, v2
	global_load_dword v42, v4, s[16:17]
	global_load_dword v43, v4, s[16:17] offset:2048
	v_add_u32_e32 v5, 0xe000, v2
	global_load_dword v44, v5, s[16:17]
	global_load_dword v45, v5, s[16:17] offset:2048
	v_add_u32_e32 v11, 0xf000, v2
	global_load_dword v46, v11, s[16:17]
	global_load_dword v47, v11, s[16:17] offset:2048
	global_load_dword v48, v2, s[4:5]
	global_load_dword v49, v2, s[4:5] offset:2048
	s_waitcnt vmcnt(26)
	v_mul_f32_e32 v50, 0xbfb8aa3b, v16
	v_mul_f32_e32 v51, 0xbfb8aa3b, v17
	v_mul_f32_e32 v52, 0xbfb8aa3b, v18
	v_mul_f32_e32 v53, 0xbfb8aa3b, v19
	v_mul_f32_e32 v54, 0xbfb8aa3b, v20
	v_mul_f32_e32 v55, 0xbfb8aa3b, v21
	v_mul_f32_e32 v56, 0xbfb8aa3b, v22
	v_mul_f32_e32 v57, 0xbfb8aa3b, v23
	v_exp_f32_e32 v50, v50
	v_exp_f32_e32 v51, v51
	v_exp_f32_e32 v52, v52
	v_exp_f32_e32 v53, v53
	v_exp_f32_e32 v54, v54
	v_exp_f32_e32 v55, v55
	v_exp_f32_e32 v56, v56
	v_exp_f32_e32 v57, v57
	v_add_f32_e32 v50, 1.0, v50
	v_add_f32_e32 v51, 1.0, v51
	v_add_f32_e32 v52, 1.0, v52
	v_add_f32_e32 v53, 1.0, v53
	v_add_f32_e32 v54, 1.0, v54
	v_add_f32_e32 v55, 1.0, v55
	v_add_f32_e32 v56, 1.0, v56
	v_add_f32_e32 v57, 1.0, v57
	v_rcp_f32_e32 v50, v50
	v_rcp_f32_e32 v51, v51
	v_rcp_f32_e32 v52, v52
	v_rcp_f32_e32 v53, v53
	v_rcp_f32_e32 v54, v54
	v_rcp_f32_e32 v55, v55
	v_rcp_f32_e32 v56, v56
	v_rcp_f32_e32 v57, v57
	v_mul_f32_e32 v16, v16, v50
	v_mul_f32_e32 v17, v17, v51
	v_mul_f32_e32 v18, v18, v52
	v_mul_f32_e32 v19, v19, v53
	v_mul_f32_e32 v20, v20, v54
	v_mul_f32_e32 v21, v21, v55
	v_mul_f32_e32 v22, v22, v56
	v_mul_f32_e32 v23, v23, v57
	ds_write_b32 v9, v16
	ds_write_b32 v9, v17 offset:2048
	ds_write_b32 v9, v18 offset:4100
	ds_write_b32 v9, v19 offset:6148
	ds_write_b32 v9, v20 offset:8200
	ds_write_b32 v9, v21 offset:10248
	ds_write_b32 v9, v22 offset:12300
	ds_write_b32 v9, v23 offset:14348
	s_waitcnt vmcnt(18)
	v_mul_f32_e32 v50, 0xbfb8aa3b, v24
	v_mul_f32_e32 v51, 0xbfb8aa3b, v25
	v_mul_f32_e32 v52, 0xbfb8aa3b, v26
	v_mul_f32_e32 v53, 0xbfb8aa3b, v27
	v_mul_f32_e32 v54, 0xbfb8aa3b, v28
	v_mul_f32_e32 v55, 0xbfb8aa3b, v29
	v_mul_f32_e32 v56, 0xbfb8aa3b, v30
	v_mul_f32_e32 v57, 0xbfb8aa3b, v31
	v_exp_f32_e32 v50, v50
	v_exp_f32_e32 v51, v51
	v_exp_f32_e32 v52, v52
	v_exp_f32_e32 v53, v53
	v_exp_f32_e32 v54, v54
	v_exp_f32_e32 v55, v55
	v_exp_f32_e32 v56, v56
	v_exp_f32_e32 v57, v57
	v_add_f32_e32 v50, 1.0, v50
	v_add_f32_e32 v51, 1.0, v51
	v_add_f32_e32 v52, 1.0, v52
	v_add_f32_e32 v53, 1.0, v53
	v_add_f32_e32 v54, 1.0, v54
	v_add_f32_e32 v55, 1.0, v55
	v_add_f32_e32 v56, 1.0, v56
	v_add_f32_e32 v57, 1.0, v57
	v_rcp_f32_e32 v50, v50
	v_rcp_f32_e32 v51, v51
	v_rcp_f32_e32 v52, v52
	v_rcp_f32_e32 v53, v53
	v_rcp_f32_e32 v54, v54
	v_rcp_f32_e32 v55, v55
	v_rcp_f32_e32 v56, v56
	v_rcp_f32_e32 v57, v57
	v_mul_f32_e32 v24, v24, v50
	v_mul_f32_e32 v25, v25, v51
	v_mul_f32_e32 v26, v26, v52
	v_mul_f32_e32 v27, v27, v53
	v_mul_f32_e32 v28, v28, v54
	v_mul_f32_e32 v29, v29, v55
	v_mul_f32_e32 v30, v30, v56
	v_mul_f32_e32 v31, v31, v57
	ds_write_b32 v9, v24 offset:16400
	ds_write_b32 v9, v25 offset:18448
	ds_write_b32 v9, v26 offset:20500
	ds_write_b32 v9, v27 offset:22548
	ds_write_b32 v9, v28 offset:24600
	ds_write_b32 v9, v29 offset:26648
	ds_write_b32 v9, v30 offset:28700
	ds_write_b32 v9, v31 offset:30748
	s_waitcnt vmcnt(10)
; __device__ __forceinline__ void p_adaln(const Args& a, unsigned char* lds, const int mk_wid) {
;     ...
;     for (int i = tid; i < 17 * 1024; i += 512) { const float v = (i < 16 * 1024) ? c[i] : cctx[i - 16 * 1024]; sl[i] = v * __builtin_amdgcn_rcpf(1.f + __expf(-v)); }
;     __syncthreads();
;     for (int w = blockIdx.x; w < 192; w += gridDim.x) {
;         const int col = w * 32 + (tid & 31), kg = tid >> 5;
;         float acc[17];
; #pragma unroll
;         for (int v = 0; v < 17; ++v) acc[v] = 0.f;
;         for (int kk = 0; kk < 64; kk += 16) { const int k = kg * 64 + kk; float wv[16];
; #pragma unroll
;             for (int j = 0; j < 16; ++j) wv[j] = __builtin_nontemporal_load(W + (size_t)(k + j) * 6144 + col);
	v_mul_f32_e32 v50, 0xbfb8aa3b, v32
	v_mul_f32_e32 v51, 0xbfb8aa3b, v33
	v_mul_f32_e32 v52, 0xbfb8aa3b, v34
	v_mul_f32_e32 v53, 0xbfb8aa3b, v35
	v_mul_f32_e32 v54, 0xbfb8aa3b, v36
	v_mul_f32_e32 v55, 0xbfb8aa3b, v37
	v_mul_f32_e32 v56, 0xbfb8aa3b, v38
	v_mul_f32_e32 v57, 0xbfb8aa3b, v39
	v_exp_f32_e32 v50, v50
	v_exp_f32_e32 v51, v51
	v_exp_f32_e32 v52, v52
	v_exp_f32_e32 v53, v53
	v_exp_f32_e32 v54, v54
	v_exp_f32_e32 v55, v55
	v_exp_f32_e32 v56, v56
	v_exp_f32_e32 v57, v57
	v_add_f32_e32 v50, 1.0, v50
	v_add_f32_e32 v51, 1.0, v51
	v_add_f32_e32 v52, 1.0, v52
	v_add_f32_e32 v53, 1.0, v53
	v_add_f32_e32 v54, 1.0, v54
	v_add_f32_e32 v55, 1.0, v55
	v_add_f32_e32 v56, 1.0, v56
	v_add_f32_e32 v57, 1.0, v57
	v_rcp_f32_e32 v50, v50
	v_rcp_f32_e32 v51, v51
	v_rcp_f32_e32 v52, v52
	v_rcp_f32_e32 v53, v53
	v_rcp_f32_e32 v54, v54
	v_rcp_f32_e32 v55, v55
	v_rcp_f32_e32 v56, v56
	v_rcp_f32_e32 v57, v57
	v_mul_f32_e32 v32, v32, v50
	v_mul_f32_e32 v33, v33, v51
	v_mul_f32_e32 v34, v34, v52
	v_mul_f32_e32 v35, v35, v53
	v_mul_f32_e32 v36, v36, v54
	v_mul_f32_e32 v37, v37, v55
	v_mul_f32_e32 v38, v38, v56
	v_mul_f32_e32 v39, v39, v57
	ds_write_b32 v9, v32 offset:32800
	ds_write_b32 v9, v33 offset:34848
	ds_write_b32 v9, v34 offset:36900
	ds_write_b32 v9, v35 offset:38948
	ds_write_b32 v9, v36 offset:41000
	ds_write_b32 v9, v37 offset:43048
	ds_write_b32 v9, v38 offset:45100
	ds_write_b32 v9, v39 offset:47148
	s_waitcnt vmcnt(2)
	v_mul_f32_e32 v50, 0xbfb8aa3b, v40
	v_mul_f32_e32 v51, 0xbfb8aa3b, v41
	v_mul_f32_e32 v52, 0xbfb8aa3b, v42
	v_mul_f32_e32 v53, 0xbfb8aa3b, v43
	v_mul_f32_e32 v54, 0xbfb8aa3b, v44
	v_mul_f32_e32 v55, 0xbfb8aa3b, v45
	v_mul_f32_e32 v56, 0xbfb8aa3b, v46
	v_mul_f32_e32 v57, 0xbfb8aa3b, v47
	v_exp_f32_e32 v50, v50
	v_exp_f32_e32 v51, v51
	v_exp_f32_e32 v52, v52
	v_exp_f32_e32 v53, v53
	v_exp_f32_e32 v54, v54
	v_exp_f32_e32 v55, v55
	v_exp_f32_e32 v56, v56
	v_exp_f32_e32 v57, v57
	v_add_f32_e32 v50, 1.0, v50
	v_add_f32_e32 v51, 1.0, v51
	v_add_f32_e32 v52, 1.0, v52
	v_add_f32_e32 v53, 1.0, v53
	v_add_f32_e32 v54, 1.0, v54
	v_add_f32_e32 v55, 1.0, v55
	v_add_f32_e32 v56, 1.0, v56
	v_add_f32_e32 v57, 1.0, v57
	v_rcp_f32_e32 v50, v50
	v_rcp_f32_e32 v51, v51
	v_rcp_f32_e32 v52, v52
	v_rcp_f32_e32 v53, v53
	v_rcp_f32_e32 v54, v54
	v_rcp_f32_e32 v55, v55
	v_rcp_f32_e32 v56, v56
	v_rcp_f32_e32 v57, v57
	v_mul_f32_e32 v40, v40, v50
	v_mul_f32_e32 v41, v41, v51
	v_mul_f32_e32 v42, v42, v52
	v_mul_f32_e32 v43, v43, v53
	v_mul_f32_e32 v44, v44, v54
	v_mul_f32_e32 v45, v45, v55
	v_mul_f32_e32 v46, v46, v56
	v_mul_f32_e32 v47, v47, v57
	ds_write_b32 v9, v40 offset:49200
	ds_write_b32 v9, v41 offset:51248
	ds_write_b32 v9, v42 offset:53300
	ds_write_b32 v9, v43 offset:55348
	ds_write_b32 v9, v44 offset:57400
	ds_write_b32 v9, v45 offset:59448
	ds_write_b32 v10, v46 offset:28732
	ds_write_b32 v10, v47 offset:30780
	s_waitcnt vmcnt(0)
	v_mul_f32_e32 v50, 0xbfb8aa3b, v48
	v_mul_f32_e32 v51, 0xbfb8aa3b, v49
	v_exp_f32_e32 v50, v50
	v_exp_f32_e32 v51, v51
	s_nop 1
	v_add_f32_e32 v50, 1.0, v50
	v_add_f32_e32 v51, 1.0, v51
	s_nop 1
	v_rcp_f32_e32 v50, v50
	v_rcp_f32_e32 v51, v51
	s_nop 1
	v_mul_f32_e32 v48, v48, v50
	v_mul_f32_e32 v49, v49, v51
	ds_write_b32 v10, v48 offset:32832
	ds_write_b32 v10, v49 offset:34880
.LBB0_12:
	s_or_b64 exec, exec, s[2:3]
	s_cmpk_gt_i32 s8, 0xbf
	s_waitcnt lgkmcnt(0)
	s_barrier
	s_cbranch_scc1 .LBB0_21
	s_mov_b32 s44, s8
.Lp0_gemv_slab:
	v_mbcnt_lo_u32_b32 v2, -1, 0
	v_mbcnt_hi_u32_b32 v2, -1, v2
	v_lshrrev_b32_e32 v3, 5, v2
	v_and_b32_e32 v4, 31, v2
	s_lshl_b32 s16, s70, 7
	v_add_u32_e32 v3, s16, v3
	v_mul_u32_u24_e32 v5, 0x6000, v3
	s_lshl_b32 s17, s44, 7
	v_lshl_add_u32 v5, v4, 2, v5
	v_add_u32_e32 v5, s17, v5
	v_mul_u32_u24_e32 v9, 0x1004, v4
	v_lshl_add_u32 v9, v3, 2, v9
	global_load_dword v16, v5, s[6:7] nt
	v_add_u32_e32 v5, 0xc000, v5
	global_load_dword v17, v5, s[6:7] nt
	v_add_u32_e32 v5, 0xc000, v5
	global_load_dword v18, v5, s[6:7] nt
	v_add_u32_e32 v5, 0xc000, v5
	global_load_dword v19, v5, s[6:7] nt
	v_add_u32_e32 v5, 0xc000, v5
	global_load_dword v20, v5, s[6:7] nt
	v_add_u32_e32 v5, 0xc000, v5
	global_load_dword v21, v5, s[6:7] nt
	v_add_u32_e32 v5, 0xc000, v5
	global_load_dword v22, v5, s[6:7] nt
	v_add_u32_e32 v5, 0xc000, v5
	global_load_dword v23, v5, s[6:7] nt
	v_add_u32_e32 v5, 0xc000, v5
	global_load_dword v24, v5, s[6:7] nt
	v_add_u32_e32 v5, 0xc000, v5
	global_load_dword v25, v5, s[6:7] nt
	v_add_u32_e32 v5, 0xc000, v5
	global_load_dword v26, v5, s[6:7] nt
	v_add_u32_e32 v5, 0xc000, v5
	global_load_dword v27, v5, s[6:7] nt
	v_add_u32_e32 v5, 0xc000, v5
	global_load_dword v28, v5, s[6:7] nt
	v_add_u32_e32 v5, 0xc000, v5
	global_load_dword v29, v5, s[6:7] nt
	v_add_u32_e32 v5, 0xc000, v5
	global_load_dword v30, v5, s[6:7] nt
	v_add_u32_e32 v5, 0xc000, v5
	global_load_dword v31, v5, s[6:7] nt
	v_add_u32_e32 v5, 0xc000, v5
	global_load_dword v32, v5, s[6:7] nt
	v_add_u32_e32 v5, 0xc000, v5
	global_load_dword v33, v5, s[6:7] nt
	v_add_u32_e32 v5, 0xc000, v5
	global_load_dword v34, v5, s[6:7] nt
	v_add_u32_e32 v5, 0xc000, v5
	global_load_dword v35, v5, s[6:7] nt
	v_add_u32_e32 v5, 0xc000, v5
	global_load_dword v36, v5, s[6:7] nt
	v_add_u32_e32 v5, 0xc000, v5
	global_load_dword v37, v5, s[6:7] nt
	v_add_u32_e32 v5, 0xc000, v5
	global_load_dword v38, v5, s[6:7] nt
	v_add_u32_e32 v5, 0xc000, v5
	global_load_dword v39, v5, s[6:7] nt
	v_add_u32_e32 v5, 0xc000, v5
	global_load_dword v40, v5, s[6:7] nt
	v_add_u32_e32 v5, 0xc000, v5
	global_load_dword v41, v5, s[6:7] nt
	v_add_u32_e32 v5, 0xc000, v5
	global_load_dword v42, v5, s[6:7] nt
	v_add_u32_e32 v5, 0xc000, v5
	global_load_dword v43, v5, s[6:7] nt
; __device__ __forceinline__ void p_adaln(const Args& a, unsigned char* lds, const int mk_wid) {
;     ...
;         for (int kk = 0; kk < 64; kk += 16) { const int k = kg * 64 + kk; float wv[16];
; #pragma unroll
;             for (int j = 0; j < 16; ++j) wv[j] = __builtin_nontemporal_load(W + (size_t)(k + j) * 6144 + col);
; #pragma unroll
;             for (int v = 0; v < 17; ++v)
; #pragma unroll
;                 for (int j4 = 0; j4 < 4; ++j4) { const f32x4 s4 = *(const f32x4*)(sl + v * 1024 + k + 4 * j4);
;                     acc[v] += (s4.x * wv[4 * j4] + s4.y * wv[4 * j4 + 1]) + (s4.z * wv[4 * j4 + 2] + s4.w * wv[4 * j4 + 3]); } }
	v_add_u32_e32 v5, 0xc000, v5
	global_load_dword v44, v5, s[6:7] nt
	v_add_u32_e32 v5, 0xc000, v5
	global_load_dword v45, v5, s[6:7] nt
	v_add_u32_e32 v5, 0xc000, v5
	global_load_dword v46, v5, s[6:7] nt
	v_add_u32_e32 v5, 0xc000, v5
	global_load_dword v47, v5, s[6:7] nt
	v_add_u32_e32 v5, 0xc000, v5
	global_load_dword v48, v5, s[6:7] nt
	v_add_u32_e32 v5, 0xc000, v5
	global_load_dword v49, v5, s[6:7] nt
	v_add_u32_e32 v5, 0xc000, v5
	global_load_dword v50, v5, s[6:7] nt
	v_add_u32_e32 v5, 0xc000, v5
	global_load_dword v51, v5, s[6:7] nt
	v_add_u32_e32 v5, 0xc000, v5
	global_load_dword v52, v5, s[6:7] nt
	v_add_u32_e32 v5, 0xc000, v5
	global_load_dword v53, v5, s[6:7] nt
	v_add_u32_e32 v5, 0xc000, v5
	global_load_dword v54, v5, s[6:7] nt
	v_add_u32_e32 v5, 0xc000, v5
	global_load_dword v55, v5, s[6:7] nt
	v_add_u32_e32 v5, 0xc000, v5
	global_load_dword v56, v5, s[6:7] nt
	v_add_u32_e32 v5, 0xc000, v5
	global_load_dword v57, v5, s[6:7] nt
	v_add_u32_e32 v5, 0xc000, v5
	global_load_dword v58, v5, s[6:7] nt
	v_add_u32_e32 v5, 0xc000, v5
	global_load_dword v59, v5, s[6:7] nt
	v_add_u32_e32 v5, 0xc000, v5
	global_load_dword v60, v5, s[6:7] nt
	v_add_u32_e32 v5, 0xc000, v5
	global_load_dword v61, v5, s[6:7] nt
	v_add_u32_e32 v5, 0xc000, v5
	global_load_dword v62, v5, s[6:7] nt
	v_add_u32_e32 v5, 0xc000, v5
	global_load_dword v63, v5, s[6:7] nt
	v_add_u32_e32 v5, 0xc000, v5
	global_load_dword v64, v5, s[6:7] nt
	v_add_u32_e32 v5, 0xc000, v5
	global_load_dword v65, v5, s[6:7] nt
	v_add_u32_e32 v5, 0xc000, v5
	global_load_dword v66, v5, s[6:7] nt
	v_add_u32_e32 v5, 0xc000, v5
	global_load_dword v67, v5, s[6:7] nt
	v_add_u32_e32 v5, 0xc000, v5
	global_load_dword v68, v5, s[6:7] nt
	v_add_u32_e32 v5, 0xc000, v5
	global_load_dword v69, v5, s[6:7] nt
	v_add_u32_e32 v5, 0xc000, v5
	global_load_dword v70, v5, s[6:7] nt
	v_add_u32_e32 v5, 0xc000, v5
	global_load_dword v71, v5, s[6:7] nt
	v_add_u32_e32 v5, 0xc000, v5
	global_load_dword v72, v5, s[6:7] nt
	v_add_u32_e32 v5, 0xc000, v5
	global_load_dword v73, v5, s[6:7] nt
	v_add_u32_e32 v5, 0xc000, v5
	global_load_dword v74, v5, s[6:7] nt
	v_add_u32_e32 v5, 0xc000, v5
	global_load_dword v75, v5, s[6:7] nt
	v_add_u32_e32 v5, 0xc000, v5
	ds_read_b32 v80, v9
	ds_read_b32 v81, v9 offset:8
	ds_read_b32 v82, v9 offset:16
	ds_read_b32 v83, v9 offset:24
	ds_read_b32 v84, v9 offset:32
	ds_read_b32 v85, v9 offset:40
	ds_read_b32 v86, v9 offset:48
	ds_read_b32 v87, v9 offset:56
	ds_read_b32 v88, v9 offset:64
	ds_read_b32 v89, v9 offset:72
	ds_read_b32 v90, v9 offset:80
	ds_read_b32 v91, v9 offset:88
	s_waitcnt vmcnt(59) lgkmcnt(11)
	v_mfma_f32_32x32x2_f32 v[144:159], v80, v16, 0
	ds_read_b32 v92, v9 offset:96
	global_load_dword v76, v5, s[6:7] nt
	v_add_u32_e32 v5, 0xc000, v5
	s_waitcnt vmcnt(59) lgkmcnt(11)
	v_mfma_f32_32x32x2_f32 v[144:159], v81, v17, v[144:159]
	ds_read_b32 v93, v9 offset:104
	global_load_dword v77, v5, s[6:7] nt
	v_add_u32_e32 v5, 0xc000, v5
	s_waitcnt vmcnt(59) lgkmcnt(11)
	v_mfma_f32_32x32x2_f32 v[144:159], v82, v18, v[144:159]
	ds_read_b32 v94, v9 offset:112
	global_load_dword v78, v5, s[6:7] nt
	v_add_u32_e32 v5, 0xc000, v5
	s_waitcnt vmcnt(59) lgkmcnt(11)
	v_mfma_f32_32x32x2_f32 v[144:159], v83, v19, v[144:159]
	ds_read_b32 v95, v9 offset:120
	global_load_dword v79, v5, s[6:7] nt
	s_waitcnt vmcnt(59) lgkmcnt(11)
	v_mfma_f32_32x32x2_f32 v[144:159], v84, v20, v[144:159]
	ds_read_b32 v96, v9 offset:128
	s_waitcnt vmcnt(58) lgkmcnt(11)
	v_mfma_f32_32x32x2_f32 v[144:159], v85, v21, v[144:159]
	ds_read_b32 v97, v9 offset:136
	s_waitcnt vmcnt(57) lgkmcnt(11)
	v_mfma_f32_32x32x2_f32 v[144:159], v86, v22, v[144:159]
	ds_read_b32 v98, v9 offset:144
	s_waitcnt vmcnt(56) lgkmcnt(11)
	v_mfma_f32_32x32x2_f32 v[144:159], v87, v23, v[144:159]
	ds_read_b32 v99, v9 offset:152
	s_waitcnt vmcnt(55) lgkmcnt(11)
	v_mfma_f32_32x32x2_f32 v[144:159], v88, v24, v[144:159]
	ds_read_b32 v100, v9 offset:160
	s_waitcnt vmcnt(54) lgkmcnt(11)
	v_mfma_f32_32x32x2_f32 v[144:159], v89, v25, v[144:159]
	ds_read_b32 v101, v9 offset:168
	s_waitcnt vmcnt(53) lgkmcnt(11)
	v_mfma_f32_32x32x2_f32 v[144:159], v90, v26, v[144:159]
	ds_read_b32 v102, v9 offset:176
	s_waitcnt vmcnt(52) lgkmcnt(11)
	v_mfma_f32_32x32x2_f32 v[144:159], v91, v27, v[144:159]
	ds_read_b32 v103, v9 offset:184
	s_waitcnt vmcnt(51) lgkmcnt(11)
	v_mfma_f32_32x32x2_f32 v[144:159], v92, v28, v[144:159]
	ds_read_b32 v104, v9 offset:192
	s_waitcnt vmcnt(50) lgkmcnt(11)
	v_mfma_f32_32x32x2_f32 v[144:159], v93, v29, v[144:159]
	ds_read_b32 v105, v9 offset:200
	s_waitcnt vmcnt(49) lgkmcnt(11)
	v_mfma_f32_32x32x2_f32 v[144:159], v94, v30, v[144:159]
	ds_read_b32 v106, v9 offset:208
	s_waitcnt vmcnt(48) lgkmcnt(11)
	v_mfma_f32_32x32x2_f32 v[144:159], v95, v31, v[144:159]
	ds_read_b32 v107, v9 offset:216
	s_waitcnt vmcnt(47) lgkmcnt(11)
	v_mfma_f32_32x32x2_f32 v[144:159], v96, v32, v[144:159]
	ds_read_b32 v108, v9 offset:224
	s_waitcnt vmcnt(46) lgkmcnt(11)
	v_mfma_f32_32x32x2_f32 v[144:159], v97, v33, v[144:159]
	ds_read_b32 v109, v9 offset:232
	s_waitcnt vmcnt(45) lgkmcnt(11)
	v_mfma_f32_32x32x2_f32 v[144:159], v98, v34, v[144:159]
	ds_read_b32 v110, v9 offset:240
	s_waitcnt vmcnt(44) lgkmcnt(11)
	v_mfma_f32_32x32x2_f32 v[144:159], v99, v35, v[144:159]
	ds_read_b32 v111, v9 offset:248
	s_waitcnt vmcnt(43) lgkmcnt(11)
	v_mfma_f32_32x32x2_f32 v[144:159], v100, v36, v[144:159]
	ds_read_b32 v112, v9 offset:256
	s_waitcnt vmcnt(42) lgkmcnt(11)
	v_mfma_f32_32x32x2_f32 v[144:159], v101, v37, v[144:159]
	ds_read_b32 v113, v9 offset:264
	s_waitcnt vmcnt(41) lgkmcnt(11)
	v_mfma_f32_32x32x2_f32 v[144:159], v102, v38, v[144:159]
	ds_read_b32 v114, v9 offset:272
	s_waitcnt vmcnt(40) lgkmcnt(11)
; __device__ __forceinline__ void p_adaln(const Args& a, unsigned char* lds, const int mk_wid) {
;     ...
;         for (int kk = 0; kk < 64; kk += 16) { const int k = kg * 64 + kk; float wv[16];
; #pragma unroll
;             for (int j = 0; j < 16; ++j) wv[j] = __builtin_nontemporal_load(W + (size_t)(k + j) * 6144 + col);
; #pragma unroll
;             for (int v = 0; v < 17; ++v)
; #pragma unroll
;                 for (int j4 = 0; j4 < 4; ++j4) { const f32x4 s4 = *(const f32x4*)(sl + v * 1024 + k + 4 * j4);
;                     acc[v] += (s4.x * wv[4 * j4] + s4.y * wv[4 * j4 + 1]) + (s4.z * wv[4 * j4 + 2] + s4.w * wv[4 * j4 + 3]); } }
; #pragma unroll
;         for (int v = 0; v < 17; ++v) part[(kg * 17 + v) * 32 + (tid & 31)] = acc[v];
;         __syncthreads();
;         for (int i = tid; i < 17 * 32; i += 512) { const int v = i >> 5, cl = i & 31; float s = bada[w * 32 + cl];
;             for (int g = 0; g < 16; ++g) s += part[(g * 17 + v) * 32 + cl];
	v_mfma_f32_32x32x2_f32 v[144:159], v103, v39, v[144:159]
	ds_read_b32 v115, v9 offset:280
	s_waitcnt vmcnt(39) lgkmcnt(11)
	v_mfma_f32_32x32x2_f32 v[144:159], v104, v40, v[144:159]
	ds_read_b32 v116, v9 offset:288
	s_waitcnt vmcnt(38) lgkmcnt(11)
	v_mfma_f32_32x32x2_f32 v[144:159], v105, v41, v[144:159]
	ds_read_b32 v117, v9 offset:296
	s_waitcnt vmcnt(37) lgkmcnt(11)
	v_mfma_f32_32x32x2_f32 v[144:159], v106, v42, v[144:159]
	ds_read_b32 v118, v9 offset:304
	s_waitcnt vmcnt(36) lgkmcnt(11)
	v_mfma_f32_32x32x2_f32 v[144:159], v107, v43, v[144:159]
	ds_read_b32 v119, v9 offset:312
	s_waitcnt vmcnt(35) lgkmcnt(11)
	v_mfma_f32_32x32x2_f32 v[144:159], v108, v44, v[144:159]
	ds_read_b32 v120, v9 offset:320
	s_waitcnt vmcnt(34) lgkmcnt(11)
	v_mfma_f32_32x32x2_f32 v[144:159], v109, v45, v[144:159]
	ds_read_b32 v121, v9 offset:328
	s_waitcnt vmcnt(33) lgkmcnt(11)
	v_mfma_f32_32x32x2_f32 v[144:159], v110, v46, v[144:159]
	ds_read_b32 v122, v9 offset:336
	s_waitcnt vmcnt(32) lgkmcnt(11)
	v_mfma_f32_32x32x2_f32 v[144:159], v111, v47, v[144:159]
	ds_read_b32 v123, v9 offset:344
	s_waitcnt vmcnt(31) lgkmcnt(11)
	v_mfma_f32_32x32x2_f32 v[144:159], v112, v48, v[144:159]
	ds_read_b32 v124, v9 offset:352
	s_waitcnt vmcnt(30) lgkmcnt(11)
	v_mfma_f32_32x32x2_f32 v[144:159], v113, v49, v[144:159]
	ds_read_b32 v125, v9 offset:360
	s_waitcnt vmcnt(29) lgkmcnt(11)
	v_mfma_f32_32x32x2_f32 v[144:159], v114, v50, v[144:159]
	ds_read_b32 v126, v9 offset:368
	s_waitcnt vmcnt(28) lgkmcnt(11)
	v_mfma_f32_32x32x2_f32 v[144:159], v115, v51, v[144:159]
	ds_read_b32 v127, v9 offset:376
	s_waitcnt vmcnt(27) lgkmcnt(11)
	v_mfma_f32_32x32x2_f32 v[144:159], v116, v52, v[144:159]
	ds_read_b32 v128, v9 offset:384
	s_waitcnt vmcnt(26) lgkmcnt(11)
	v_mfma_f32_32x32x2_f32 v[144:159], v117, v53, v[144:159]
	ds_read_b32 v129, v9 offset:392
	s_waitcnt vmcnt(25) lgkmcnt(11)
	v_mfma_f32_32x32x2_f32 v[144:159], v118, v54, v[144:159]
	ds_read_b32 v130, v9 offset:400
	s_waitcnt vmcnt(24) lgkmcnt(11)
	v_mfma_f32_32x32x2_f32 v[144:159], v119, v55, v[144:159]
	ds_read_b32 v131, v9 offset:408
	s_waitcnt vmcnt(23) lgkmcnt(11)
	v_mfma_f32_32x32x2_f32 v[144:159], v120, v56, v[144:159]
	ds_read_b32 v132, v9 offset:416
	s_waitcnt vmcnt(22) lgkmcnt(11)
	v_mfma_f32_32x32x2_f32 v[144:159], v121, v57, v[144:159]
	ds_read_b32 v133, v9 offset:424
	s_waitcnt vmcnt(21) lgkmcnt(11)
	v_mfma_f32_32x32x2_f32 v[144:159], v122, v58, v[144:159]
	ds_read_b32 v134, v9 offset:432
	s_waitcnt vmcnt(20) lgkmcnt(11)
	v_mfma_f32_32x32x2_f32 v[144:159], v123, v59, v[144:159]
	ds_read_b32 v135, v9 offset:440
	s_waitcnt vmcnt(19) lgkmcnt(11)
	v_mfma_f32_32x32x2_f32 v[144:159], v124, v60, v[144:159]
	ds_read_b32 v136, v9 offset:448
	s_waitcnt vmcnt(18) lgkmcnt(11)
	v_mfma_f32_32x32x2_f32 v[144:159], v125, v61, v[144:159]
	ds_read_b32 v137, v9 offset:456
	s_waitcnt vmcnt(17) lgkmcnt(11)
	v_mfma_f32_32x32x2_f32 v[144:159], v126, v62, v[144:159]
	ds_read_b32 v138, v9 offset:464
	s_waitcnt vmcnt(16) lgkmcnt(11)
	v_mfma_f32_32x32x2_f32 v[144:159], v127, v63, v[144:159]
	ds_read_b32 v139, v9 offset:472
	s_waitcnt vmcnt(15) lgkmcnt(11)
	v_mfma_f32_32x32x2_f32 v[144:159], v128, v64, v[144:159]
	ds_read_b32 v140, v9 offset:480
	s_waitcnt vmcnt(14) lgkmcnt(11)
	v_mfma_f32_32x32x2_f32 v[144:159], v129, v65, v[144:159]
	ds_read_b32 v141, v9 offset:488
	s_waitcnt vmcnt(13) lgkmcnt(11)
	v_mfma_f32_32x32x2_f32 v[144:159], v130, v66, v[144:159]
	ds_read_b32 v142, v9 offset:496
	s_waitcnt vmcnt(12) lgkmcnt(11)
	v_mfma_f32_32x32x2_f32 v[144:159], v131, v67, v[144:159]
	ds_read_b32 v143, v9 offset:504
	s_waitcnt vmcnt(11) lgkmcnt(11)
	v_mfma_f32_32x32x2_f32 v[144:159], v132, v68, v[144:159]
	s_waitcnt vmcnt(10) lgkmcnt(10)
	v_mfma_f32_32x32x2_f32 v[144:159], v133, v69, v[144:159]
	s_waitcnt vmcnt(9) lgkmcnt(9)
	v_mfma_f32_32x32x2_f32 v[144:159], v134, v70, v[144:159]
	s_waitcnt vmcnt(8) lgkmcnt(8)
	v_mfma_f32_32x32x2_f32 v[144:159], v135, v71, v[144:159]
	s_waitcnt vmcnt(7) lgkmcnt(7)
	v_mfma_f32_32x32x2_f32 v[144:159], v136, v72, v[144:159]
	s_waitcnt vmcnt(6) lgkmcnt(6)
	v_mfma_f32_32x32x2_f32 v[144:159], v137, v73, v[144:159]
	s_waitcnt vmcnt(5) lgkmcnt(5)
	v_mfma_f32_32x32x2_f32 v[144:159], v138, v74, v[144:159]
	s_waitcnt vmcnt(4) lgkmcnt(4)
	v_mfma_f32_32x32x2_f32 v[144:159], v139, v75, v[144:159]
	s_waitcnt vmcnt(3) lgkmcnt(3)
	v_mfma_f32_32x32x2_f32 v[144:159], v140, v76, v[144:159]
	s_waitcnt vmcnt(2) lgkmcnt(2)
	v_mfma_f32_32x32x2_f32 v[144:159], v141, v77, v[144:159]
	s_waitcnt vmcnt(1) lgkmcnt(1)
	v_mfma_f32_32x32x2_f32 v[144:159], v142, v78, v[144:159]
	s_waitcnt vmcnt(0) lgkmcnt(0)
	v_mfma_f32_32x32x2_f32 v[144:159], v143, v79, v[144:159]
	s_lshl_b32 s16, s70, 12
	s_add_i32 s16, s16, 0x11800
	v_lshl_add_u32 v10, v2, 2, s16
	s_nop 15
	s_nop 1
	ds_write_b32 v10, v144
	ds_write_b32 v10, v145 offset:256
	ds_write_b32 v10, v146 offset:512
	ds_write_b32 v10, v147 offset:768
	ds_write_b32 v10, v148 offset:1024
	ds_write_b32 v10, v149 offset:1280
	ds_write_b32 v10, v150 offset:1536
	ds_write_b32 v10, v151 offset:1792
	s_waitcnt lgkmcnt(4)
	ds_write_b32 v10, v152 offset:2048
	ds_write_b32 v10, v153 offset:2304
	ds_write_b32 v10, v154 offset:2560
	ds_write_b32 v10, v155 offset:2816
	ds_write_b32 v10, v156 offset:3072
	ds_write_b32 v10, v157 offset:3328
	ds_write_b32 v10, v158 offset:3584
	ds_write_b32 v10, v159 offset:3840
	v_add_u32_e32 v11, s72, v2
	v_lshrrev_b32_e32 v12, 5, v11
	v_and_b32_e32 v13, 3, v12
	v_lshrrev_b32_e32 v15, 2, v12
	v_lshl_add_u32 v13, v15, 3, v13
	v_bfe_u32 v15, v11, 4, 1
	v_lshl_add_u32 v13, v15, 2, v13
	v_and_b32_e32 v15, 15, v11
	v_lshlrev_b32_e32 v15, 3, v15
	v_add_u32_e32 v15, s17, v15
	global_load_dwordx2 v[160:161], v15, s[14:15]
	v_mul_u32_u24_e32 v162, 0x6000, v13
	v_add_u32_e32 v162, v162, v15
	v_lshlrev_b32_e32 v163, 3, v11
	v_add_u32_e32 v163, 0x11800, v163
	s_waitcnt lgkmcnt(0)
	s_barrier
; __device__ __forceinline__ void p_adaln(const Args& a, unsigned char* lds, const int mk_wid) {
;     ...
;         for (int v = 0; v < 17; ++v) part[(kg * 17 + v) * 32 + (tid & 31)] = acc[v];
;         __syncthreads();
;         for (int i = tid; i < 17 * 32; i += 512) { const int v = i >> 5, cl = i & 31; float s = bada[w * 32 + cl];
;             for (int g = 0; g < 16; ++g) s += part[(g * 17 + v) * 32 + cl];
;             MOD[v * 6144 + w * 32 + cl] = s; }
;         __syncthreads();
;     }
	ds_read_b64 v[164:165], v163
	ds_read_b64 v[166:167], v163 offset:4096
	ds_read_b64 v[168:169], v163 offset:8192
	ds_read_b64 v[170:171], v163 offset:12288
	ds_read_b64 v[172:173], v163 offset:16384
	ds_read_b64 v[174:175], v163 offset:20480
	ds_read_b64 v[176:177], v163 offset:24576
	ds_read_b64 v[178:179], v163 offset:28672
	s_waitcnt lgkmcnt(6)
	v_add_f32_e32 v164, v164, v166
	v_add_f32_e32 v165, v165, v167
	s_waitcnt lgkmcnt(5)
	v_add_f32_e32 v164, v164, v168
	v_add_f32_e32 v165, v165, v169
	s_waitcnt lgkmcnt(4)
	v_add_f32_e32 v164, v164, v170
	v_add_f32_e32 v165, v165, v171
	s_waitcnt lgkmcnt(3)
	v_add_f32_e32 v164, v164, v172
	v_add_f32_e32 v165, v165, v173
	s_waitcnt lgkmcnt(2)
	v_add_f32_e32 v164, v164, v174
	v_add_f32_e32 v165, v165, v175
	s_waitcnt lgkmcnt(1)
	v_add_f32_e32 v164, v164, v176
	v_add_f32_e32 v165, v165, v177
	s_waitcnt lgkmcnt(0)
	v_add_f32_e32 v164, v164, v178
	v_add_f32_e32 v165, v165, v179
	s_waitcnt vmcnt(0)
	v_add_f32_e32 v164, v164, v160
	v_add_f32_e32 v165, v165, v161
	v_cmp_gt_u32_e32 vcc, 17, v13
	s_and_saveexec_b64 s[16:17], vcc
	s_add_u32 s18, s38, 0x100000
	s_addc_u32 s19, s39, 0
	global_store_dwordx2 v162, v[164:165], s[18:19]
	s_or_b64 exec, exec, s[16:17]
	s_add_i32 s44, s44, s36
	s_cmpk_gt_i32 s44, 0xbf
	s_barrier
	s_cbranch_scc0 .Lp0_gemv_slab
